# adds seam prefetch: before the barrier between GEMM phases each wave touches an 8 KiB slice of the next phase's first weight K-tiles (L2 warm-up); barrier leading waits vmcnt(1)
# speedup vs baseline: 1.0025x; 1.0025x over previous
.LBB0_603:
	v_readfirstlane_b32 s100, v240
	v_readlane_b32 s98, v254, 19
	v_readlane_b32 s99, v254, 20
	v_readlane_b32 s32, v253, 36
	v_readlane_b32 s101, v253, 31
	s_lshr_b32 s100, s100, 7
	s_cmp_eq_u32 s100, 1
	s_cselect_b32 s32, s101, s32
	v_readlane_b32 s101, v253, 33
	s_cmp_eq_u32 s100, 2
	s_cselect_b32 s32, s101, s32
	v_readlane_b32 s101, v253, 37
	s_cmp_eq_u32 s100, 3
	s_cselect_b32 s32, s101, s32
	s_add_u32 s98, s98, 0x2600000
	s_addc_u32 s99, s99, 0
	v_and_b32_e32 v96, 0x7f, v240
	v_lshlrev_b32_e32 v96, 7, v96
	v_add_u32_e32 v96, s32, v96
	v_mov_b32_e32 v97, 0
	v_lshl_add_u64 v[96:97], s[98:99], 0, v[96:97]
	global_load_dword v98, v[96:97], off
	v_readlane_b32 s0, v254, 18
	s_add_i32 s16, s0, 4
	s_cmp_ge_i32 s16, s91
	s_cbranch_scc1 .LBB0_675
	v_readlane_b32 s2, v250, 55
	v_readlane_b32 s3, v250, 56
	s_mov_b64 s[0:1], -1
	s_and_b64 vcc, exec, s[2:3]
	s_cbranch_vccz .LBB0_659
	s_waitcnt vmcnt(1)
	v_readlane_b32 s0, v251, 12
	v_readlane_b32 s1, v251, 13
	s_andn2_b64 vcc, exec, s[0:1]
	s_waitcnt lgkmcnt(0)
	s_barrier
	s_cbranch_vccnz .LBB0_658
	v_mov_b32_e32 v0, v81
	s_nop 0
	v_mbcnt_lo_u32_b32 v0, -1, v0
	v_mbcnt_hi_u32_b32 v0, -1, v0
	v_cmp_eq_u32_e32 vcc, 0, v0
	s_and_saveexec_b64 s[0:1], vcc
	s_cbranch_execz .LBB0_657
	v_readlane_b32 s2, v250, 5
	s_waitcnt vmcnt(0) expcnt(0) lgkmcnt(0)
	s_nop 0
	v_mov_b32_e32 v0, s2
	ds_read_b32 v2, v0
	ds_read_b32 v0, v0 offset:4
	s_waitcnt lgkmcnt(1)
	v_cmp_ne_u32_e32 vcc, 0, v2
	s_cbranch_vccnz .LBB0_625
	v_readlane_b32 s4, v250, 0
	v_readlane_b32 s5, v250, 1
	s_load_dwordx2 s[2:3], s[4:5], 0x4
	s_mov_b32 s9, 1
	s_waitcnt lgkmcnt(0)
	s_mul_i32 s8, s2, s33
	s_mul_i32 s8, s8, s3
	s_branch .LBB0_610

.LBB0_659:
	s_and_b64 vcc, exec, s[0:1]
	s_cbranch_vccz .LBB0_675
	s_waitcnt vmcnt(1)
	v_readlane_b32 s0, v251, 12
	v_readlane_b32 s1, v251, 13
	s_andn2_b64 vcc, exec, s[0:1]
	s_waitcnt lgkmcnt(0)
	s_barrier
	s_cbranch_vccnz .LBB0_674
	v_mov_b32_e32 v0, v81
	s_nop 0
	v_mbcnt_lo_u32_b32 v0, -1, v0
	v_mbcnt_hi_u32_b32 v0, -1, v0
	v_cmp_eq_u32_e32 vcc, 0, v0
	s_and_saveexec_b64 s[0:1], vcc
	s_cbranch_execz .LBB0_673
	v_readlane_b32 s4, v254, 2
	s_mov_b64 s[2:3], exec
	v_mbcnt_lo_u32_b32 v1, s2, 0
	v_mov_b32_e32 v0, s4
	ds_read_b32 v0, v0
	v_mbcnt_hi_u32_b32 v1, s3, v1
	v_cmp_eq_u32_e32 vcc, 0, v1
	s_and_saveexec_b64 s[4:5], vcc
	s_cbranch_execz .LBB0_664
	s_bcnt1_i32_b64 s2, s[2:3]
	v_mov_b32_e32 v1, s2
	v_readlane_b32 s2, v252, 38
	v_readlane_b32 s3, v252, 39
	s_nop 4
	global_atomic_add v81, v1, s[2:3]

.LBB0_714:
	v_readfirstlane_b32 s100, v240
	v_readlane_b32 s98, v254, 19
	v_readlane_b32 s99, v254, 20
	v_readlane_b32 s32, v253, 20
	v_readlane_b32 s101, v253, 14
	s_lshr_b32 s100, s100, 7
	s_cmp_eq_u32 s100, 1
	s_cselect_b32 s32, s101, s32
	v_readlane_b32 s101, v253, 17
	s_cmp_eq_u32 s100, 2
	s_cselect_b32 s32, s101, s32
	v_readlane_b32 s101, v253, 21
	s_cmp_eq_u32 s100, 3
	s_cselect_b32 s32, s101, s32
	s_add_u32 s98, s98, 0x2e00000
	s_addc_u32 s99, s99, 0
	v_and_b32_e32 v96, 0x7f, v240
	v_lshlrev_b32_e32 v96, 7, v96
	v_add_u32_e32 v96, s32, v96
	v_mov_b32_e32 v97, 0
	v_lshl_add_u64 v[96:97], s[98:99], 0, v[96:97]
	global_load_dword v98, v[96:97], off
	v_readlane_b32 s0, v254, 18
	s_add_i32 s16, s0, 5
	s_cmp_ge_i32 s16, s91
	s_cbranch_scc1 .LBB0_783
	v_readlane_b32 s2, v250, 55
	v_readlane_b32 s3, v250, 56
	s_mov_b64 s[0:1], -1
	s_and_b64 vcc, exec, s[2:3]
	s_cbranch_vccz .LBB0_767
	s_waitcnt vmcnt(1)
	v_readlane_b32 s0, v251, 12
	v_readlane_b32 s1, v251, 13
	s_andn2_b64 vcc, exec, s[0:1]
	s_waitcnt lgkmcnt(0)
	s_barrier
	s_cbranch_vccnz .LBB0_766
	v_mov_b32_e32 v0, v81
	s_nop 0
	v_mbcnt_lo_u32_b32 v0, -1, v0
	v_mbcnt_hi_u32_b32 v0, -1, v0
	v_cmp_eq_u32_e32 vcc, 0, v0
	s_and_saveexec_b64 s[0:1], vcc
	s_cbranch_execz .LBB0_765
	v_readlane_b32 s2, v250, 5
	s_waitcnt vmcnt(0) expcnt(0) lgkmcnt(0)
	s_nop 0
	v_mov_b32_e32 v0, s2
	ds_read_b32 v2, v0
	ds_read_b32 v0, v0 offset:4
	s_waitcnt lgkmcnt(1)
	v_cmp_ne_u32_e32 vcc, 0, v2
	s_cbranch_vccnz .LBB0_733
	v_readlane_b32 s4, v250, 0
	v_readlane_b32 s5, v250, 1
	s_load_dwordx2 s[2:3], s[4:5], 0x4
	s_mov_b32 s9, 1
	s_waitcnt lgkmcnt(0)
	s_mul_i32 s8, s2, s33
	s_mul_i32 s8, s8, s3
	s_branch .LBB0_721

.LBB0_802:
	v_readfirstlane_b32 s100, v240
	v_readlane_b32 s98, v254, 19
	v_readlane_b32 s99, v254, 20
	v_readlane_b32 s32, v253, 45
	v_readlane_b32 s101, v253, 39
	s_lshr_b32 s100, s100, 7
	s_cmp_eq_u32 s100, 1
	s_cselect_b32 s32, s101, s32
	v_readlane_b32 s101, v253, 42
	s_cmp_eq_u32 s100, 2
	s_cselect_b32 s32, s101, s32
	v_readlane_b32 s101, v253, 46
	s_cmp_eq_u32 s100, 3
	s_cselect_b32 s32, s101, s32
	s_add_u32 s98, s98, 0x5a00000
	s_addc_u32 s99, s99, 0
	v_and_b32_e32 v96, 0x7f, v240
	v_lshlrev_b32_e32 v96, 7, v96
	v_add_u32_e32 v96, s32, v96
	v_mov_b32_e32 v97, 0
	v_lshl_add_u64 v[96:97], s[98:99], 0, v[96:97]
	global_load_dword v98, v[96:97], off
	v_readlane_b32 s0, v254, 18
	s_add_i32 s16, s0, 6
	s_cmp_ge_i32 s16, s91
	s_cbranch_scc1 .LBB0_871
	v_readlane_b32 s2, v250, 55
	v_readlane_b32 s3, v250, 56
	s_mov_b64 s[0:1], -1
	s_and_b64 vcc, exec, s[2:3]
	s_cbranch_vccz .LBB0_855
	s_waitcnt vmcnt(1)
	v_readlane_b32 s0, v251, 12
	v_readlane_b32 s1, v251, 13
	s_andn2_b64 vcc, exec, s[0:1]
	s_waitcnt lgkmcnt(0)
	s_barrier
	s_cbranch_vccnz .LBB0_854
	v_mov_b32_e32 v0, v81
	s_nop 0
	v_mbcnt_lo_u32_b32 v0, -1, v0
	v_mbcnt_hi_u32_b32 v0, -1, v0
	v_cmp_eq_u32_e32 vcc, 0, v0
	s_and_saveexec_b64 s[0:1], vcc
	s_cbranch_execz .LBB0_853
	v_readlane_b32 s2, v250, 5
	s_waitcnt vmcnt(0) expcnt(0) lgkmcnt(0)
	s_nop 0
	v_mov_b32_e32 v0, s2
	ds_read_b32 v2, v0
	ds_read_b32 v0, v0 offset:4
	s_waitcnt lgkmcnt(1)
	v_cmp_ne_u32_e32 vcc, 0, v2
	s_cbranch_vccnz .LBB0_821
	v_readlane_b32 s4, v250, 0
	v_readlane_b32 s5, v250, 1
	s_load_dwordx2 s[2:3], s[4:5], 0x4
	s_mov_b32 s9, 1
	s_waitcnt lgkmcnt(0)
	s_mul_i32 s8, s2, s33
	s_mul_i32 s8, s8, s3
	s_branch .LBB0_809
